# final/prologue RMSNorm loops: loop-invariant gain loads hoisted, row loads issued together; NSA top-k bit search fully unrolled
# speedup vs baseline: 1.0523x; 1.0050x over previous
; __device__ __forceinline__ unsigned pk2(float lo, float hi) { const f32x2_t v = {lo, hi}; const bf16v2_t b = __builtin_convertvector(v, bf16v2_t); return __builtin_bit_cast(unsigned, b); }
; __device__ __forceinline__ void rms_row_bf16(const float* xrow, const float* g, bf16_t* orow, int lane) {
;     f32x4 v[4]; float s = 0.f;
; #pragma unroll
;     for (int j = 0; j < 4; ++j) { v[j] = ((const f32x4*)xrow)[lane + 64 * j]; s += (v[j].x * v[j].x + v[j].y * v[j].y) + (v[j].z * v[j].z + v[j].w * v[j].w); }
;     const float r = rsqrtf(wave_sum(s) * (1.f / DM) + EPSN);
; #pragma unroll
;     for (int j = 0; j < 4; ++j) { const f32x4 gv = ((const f32x4*)g)[lane + 64 * j]; u32x2 o; o.x = pk2(v[j].x * r * gv.x, v[j].y * r * gv.y); o.y = pk2(v[j].z * r * gv.z, v[j].w * r * gv.w);
;         ((u32x2*)orow)[lane + 64 * j] = o; }
; }
; __device__ __forceinline__ void phase_norm_bf16(const Params& p, const float* x, const float* g, bf16_t* H, int wid, int lane) {
;     for (int m = p.bid * 8 + wid; m < NT; m += p.gdim * 8) rms_row_bf16(x + (size_t)m * DM, g, H + (size_t)m * DM, lane);
; }
.LBB0_65:
	s_or_b64 exec, exec, s[2:3]
	v_readlane_b32 s0, v254, 3
	v_readlane_b32 s86, v254, 9
	s_cmpk_gt_i32 s38, 0x7fff
	v_readlane_b32 s1, v254, 4
	v_readlane_b32 s87, v254, 10
	s_cbranch_scc1 .LBB0_68
	v_mbcnt_lo_u32_b32 v3, -1, 0
	v_mbcnt_hi_u32_b32 v3, -1, v3
	v_and_b32_e32 v4, 64, v3
	v_add_u32_e32 v4, 64, v4
	v_xor_b32_e32 v5, 1, v3
	v_cmp_lt_i32_e32 vcc, v5, v4
	s_ashr_i32 s2, s21, 31
	s_ashr_i32 s3, s39, 31
	v_cndmask_b32_e32 v5, v3, v5, vcc
	v_lshlrev_b32_e32 v8, 2, v5
	v_xor_b32_e32 v5, 2, v3
	v_cmp_lt_i32_e32 vcc, v5, v4
	s_add_u32 s4, s21, s39
	s_addc_u32 s5, s2, s3
	v_cndmask_b32_e32 v5, v3, v5, vcc
	v_lshlrev_b32_e32 v9, 2, v5
	v_xor_b32_e32 v5, 4, v3
	v_cmp_lt_i32_e32 vcc, v5, v4
	s_lshl_b64 s[2:3], s[4:5], 12
	s_add_u32 s2, s12, s2
	v_cndmask_b32_e32 v5, v3, v5, vcc
	v_lshlrev_b32_e32 v10, 2, v5
	v_xor_b32_e32 v5, 8, v3
	v_cmp_lt_i32_e32 vcc, v5, v4
	v_lshlrev_b32_e32 v14, 4, v1
	v_mov_b32_e32 v15, 0
	v_cndmask_b32_e32 v5, v3, v5, vcc
	v_lshlrev_b32_e32 v11, 2, v5
	v_xor_b32_e32 v5, 16, v3
	v_cmp_lt_i32_e32 vcc, v5, v4
	s_addc_u32 s3, s13, s3
	v_lshl_add_u64 v[6:7], s[2:3], 0, v[14:15]
	v_cndmask_b32_e32 v5, v3, v5, vcc
	v_lshlrev_b32_e32 v12, 2, v5
	v_xor_b32_e32 v5, 32, v3
	s_mov_b64 s[2:3], 0x800
	s_ashr_i32 s21, s20, 31
	v_cmp_lt_i32_e32 vcc, v5, v4
	v_lshl_add_u64 v[6:7], v[6:7], 0, s[2:3]
	s_lshl_b64 s[2:3], s[20:21], 12
	s_lshl_b64 s[4:5], s[4:5], 11
	v_cndmask_b32_e32 v3, v3, v5, vcc
	s_add_u32 s4, s22, s4
	v_lshlrev_b32_e32 v13, 2, v3
	v_mov_b32_e32 v3, v15
	s_addc_u32 s5, s23, s5
	v_lshl_add_u64 v[2:3], s[4:5], 0, v[2:3]
	s_mov_b64 s[4:5], 0x10000400
	v_lshl_add_u64 v[4:5], s[14:15], 0, v[14:15]
	v_lshl_add_u64 v[2:3], v[2:3], 0, s[4:5]
	s_lshl_b64 s[4:5], s[20:21], 11
	v_mov_b32_e32 v1, 0x358637bd
	s_mov_b32 s6, 0x800000
	global_load_dwordx4 v[60:63], v[4:5], off offset:1024
	global_load_dwordx4 v[64:67], v[4:5], off offset:2048
	global_load_dwordx4 v[68:71], v[4:5], off offset:3072
	s_waitcnt vmcnt(0)
.LBB0_67:
	global_load_dwordx4 v[14:17], v[6:7], off offset:-2048
	global_load_dwordx4 v[18:21], v[6:7], off offset:-1024
	global_load_dwordx4 v[22:25], v[6:7], off
	global_load_dwordx4 v[26:29], v[6:7], off offset:1024
	global_load_dwordx4 v[30:33], v[4:5], off
	s_add_i32 s38, s38, s20
	v_lshl_add_u64 v[6:7], v[6:7], 0, s[2:3]
	s_cmp_lt_i32 s38, 0x8000
	s_waitcnt vmcnt(4)
	v_pk_mul_f32 v[34:35], v[16:17], v[16:17]
	v_pk_mul_f32 v[36:37], v[14:15], v[14:15]
	s_waitcnt vmcnt(3)
	v_pk_mul_f32 v[38:39], v[20:21], v[20:21]
	v_pk_mul_f32 v[40:41], v[18:19], v[18:19]
	v_pk_mov_b32 v[46:47], v[36:37], v[34:35] op_sel:[1,0]
	v_mov_b32_e32 v37, v35
	v_pk_mov_b32 v[34:35], v[40:41], v[38:39] op_sel:[1,0]
	v_mov_b32_e32 v41, v39
	s_waitcnt vmcnt(1)
	v_mul_f32_e32 v45, v26, v26
	v_mul_f32_e32 v42, v23, v23
	v_mul_f32_e32 v44, v25, v25
	v_pk_add_f32 v[36:37], v[46:47], v[36:37]
	v_pk_add_f32 v[34:35], v[34:35], v[40:41]
	v_mul_f32_e32 v48, v27, v27
	v_mul_f32_e32 v49, v28, v28
	v_mul_f32_e32 v50, v29, v29
	v_pk_fma_f32 v[38:39], v[22:23], v[22:23], v[42:43] op_sel_hi:[1,1,0]
	v_pk_fma_f32 v[42:43], v[24:25], v[24:25], v[44:45] op_sel_hi:[1,1,0]
	v_pk_add_f32 v[36:37], v[36:37], v[36:37] op_sel:[0,1] op_sel_hi:[1,0]
	v_pk_add_f32 v[34:35], v[34:35], v[34:35] op_sel:[0,1] op_sel_hi:[1,0]
	v_mov_b32_e32 v39, v49
	v_mov_b32_e32 v43, v50
	v_mov_b32_e32 v37, v45
	v_mov_b32_e32 v35, v48
	v_pk_add_f32 v[38:39], v[38:39], v[42:43]
	v_pk_add_f32 v[34:35], v[36:37], v[34:35]
	s_nop 0
	v_pk_add_f32 v[34:35], v[34:35], v[38:39]
	s_nop 0
	v_add_f32_e32 v34, v34, v35
	ds_bpermute_b32 v35, v8, v34
	s_waitcnt lgkmcnt(0)
	v_add_f32_e32 v34, v34, v35
	ds_bpermute_b32 v35, v9, v34
	s_waitcnt lgkmcnt(0)
	v_add_f32_e32 v34, v34, v35
	ds_bpermute_b32 v35, v10, v34
	s_waitcnt lgkmcnt(0)
	v_add_f32_e32 v34, v34, v35
	ds_bpermute_b32 v35, v11, v34
	s_waitcnt lgkmcnt(0)
	v_add_f32_e32 v34, v34, v35
	ds_bpermute_b32 v35, v12, v34
	s_waitcnt lgkmcnt(0)
	v_add_f32_e32 v34, v34, v35
	ds_bpermute_b32 v35, v13, v34
	s_waitcnt lgkmcnt(0)
	v_add_f32_e32 v34, v34, v35
	v_fmamk_f32 v34, v34, 0x3a800000, v1
	v_mul_f32_e32 v35, 0x4b800000, v34
	v_cmp_gt_f32_e32 vcc, s6, v34
	s_nop 1
	v_cndmask_b32_e32 v34, v34, v35, vcc
	v_rsq_f32_e32 v34, v34
	s_nop 0
	v_mul_f32_e32 v35, 0x45800000, v34
	v_cndmask_b32_e32 v34, v34, v35, vcc
	v_pk_mul_f32 v[14:15], v[14:15], v[34:35] op_sel_hi:[1,0]
	v_pk_mul_f32 v[16:17], v[16:17], v[34:35] op_sel_hi:[1,0]
	s_waitcnt vmcnt(0)
	v_pk_mul_f32 v[14:15], v[30:31], v[14:15]
	v_pk_mul_f32 v[16:17], v[32:33], v[16:17]
	v_cvt_pk_bf16_f32 v14, v14, v15
	v_cvt_pk_bf16_f32 v15, v16, v17
	global_store_dwordx2 v[2:3], v[14:15], off offset:-1024
	v_pk_mul_f32 v[18:19], v[18:19], v[34:35] op_sel_hi:[1,0]
	v_pk_mul_f32 v[20:21], v[20:21], v[34:35] op_sel_hi:[1,0]
	v_pk_mul_f32 v[14:15], v[60:61], v[18:19]
	v_pk_mul_f32 v[16:17], v[62:63], v[20:21]
	v_cvt_pk_bf16_f32 v14, v14, v15
	v_cvt_pk_bf16_f32 v15, v16, v17
	global_store_dwordx2 v[2:3], v[14:15], off offset:-512
	v_pk_mul_f32 v[18:19], v[22:23], v[34:35] op_sel_hi:[1,0]
	v_pk_mul_f32 v[20:21], v[24:25], v[34:35] op_sel_hi:[1,0]
	v_pk_mul_f32 v[14:15], v[64:65], v[18:19]
	v_pk_mul_f32 v[16:17], v[66:67], v[20:21]
	v_cvt_pk_bf16_f32 v14, v14, v15
	v_cvt_pk_bf16_f32 v15, v16, v17
	global_store_dwordx2 v[2:3], v[14:15], off
	v_pk_mul_f32 v[18:19], v[26:27], v[34:35] op_sel_hi:[1,0]
	v_pk_mul_f32 v[20:21], v[28:29], v[34:35] op_sel_hi:[1,0]
	v_pk_mul_f32 v[14:15], v[68:69], v[18:19]
	v_pk_mul_f32 v[16:17], v[70:71], v[20:21]
	v_cvt_pk_bf16_f32 v14, v14, v15
	v_cvt_pk_bf16_f32 v15, v16, v17
	global_store_dwordx2 v[2:3], v[14:15], off offset:512
	v_lshl_add_u64 v[2:3], v[2:3], 0, s[4:5]
	s_cbranch_scc1 .LBB0_67

; __device__ __forceinline__ void phase_cmp(const Params& p, LAS unsigned char* lds, const bf16_t* Z, const float* G, const bf16_t* KC, const bf16_t* ACCW, float* ACC, int* IDX, ...
;     ...
; #pragma unroll
;                     for (int i = 0; i < 4; ++i) cnt += __builtin_popcountll(__ballot(ok[i] && v[i] >= trial));
;                     if (cnt >= 13) T = trial; }
.LBB0_433:
	s_waitcnt lgkmcnt(0)
	s_or_b32 s23, s96, 0x40000000
	v_cmp_le_u32_e64 s[20:21], s23, v2
	v_cmp_le_u32_e64 s[98:99], s23, v5
	v_cmp_le_u32_e64 s[100:101], s23, v4
	s_bcnt1_i32_b64 s24, s[20:21]
	v_cmp_le_u32_e64 s[20:21], s23, v0
	s_bcnt1_i32_b64 s25, s[98:99]
	s_add_i32 s24, s24, s25
	s_bcnt1_i32_b64 s25, s[100:101]
	s_add_i32 s24, s24, s25
	s_bcnt1_i32_b64 s25, s[20:21]
	s_add_i32 s24, s24, s25
	s_cmp_gt_u32 s24, 12
	s_cselect_b32 s96, s23, s96
	s_or_b32 s23, s96, 0x20000000
	v_cmp_le_u32_e64 s[20:21], s23, v2
	v_cmp_le_u32_e64 s[98:99], s23, v5
	v_cmp_le_u32_e64 s[100:101], s23, v4
	s_bcnt1_i32_b64 s24, s[20:21]
	v_cmp_le_u32_e64 s[20:21], s23, v0
	s_bcnt1_i32_b64 s25, s[98:99]
	s_add_i32 s24, s24, s25
	s_bcnt1_i32_b64 s25, s[100:101]
	s_add_i32 s24, s24, s25
	s_bcnt1_i32_b64 s25, s[20:21]
	s_add_i32 s24, s24, s25
	s_cmp_gt_u32 s24, 12
	s_cselect_b32 s96, s23, s96
	s_or_b32 s23, s96, 0x10000000
	v_cmp_le_u32_e64 s[20:21], s23, v2
	v_cmp_le_u32_e64 s[98:99], s23, v5
	v_cmp_le_u32_e64 s[100:101], s23, v4
	s_bcnt1_i32_b64 s24, s[20:21]
	v_cmp_le_u32_e64 s[20:21], s23, v0
	s_bcnt1_i32_b64 s25, s[98:99]
	s_add_i32 s24, s24, s25
	s_bcnt1_i32_b64 s25, s[100:101]
	s_add_i32 s24, s24, s25
	s_bcnt1_i32_b64 s25, s[20:21]
	s_add_i32 s24, s24, s25
	s_cmp_gt_u32 s24, 12
	s_cselect_b32 s96, s23, s96
	s_or_b32 s23, s96, 0x8000000
	v_cmp_le_u32_e64 s[20:21], s23, v2
	v_cmp_le_u32_e64 s[98:99], s23, v5
	v_cmp_le_u32_e64 s[100:101], s23, v4
	s_bcnt1_i32_b64 s24, s[20:21]
	v_cmp_le_u32_e64 s[20:21], s23, v0
	s_bcnt1_i32_b64 s25, s[98:99]
	s_add_i32 s24, s24, s25
	s_bcnt1_i32_b64 s25, s[100:101]
	s_add_i32 s24, s24, s25
	s_bcnt1_i32_b64 s25, s[20:21]
	s_add_i32 s24, s24, s25
	s_cmp_gt_u32 s24, 12
	s_cselect_b32 s96, s23, s96
	s_or_b32 s23, s96, 0x4000000
	v_cmp_le_u32_e64 s[20:21], s23, v2
	v_cmp_le_u32_e64 s[98:99], s23, v5
	v_cmp_le_u32_e64 s[100:101], s23, v4
	s_bcnt1_i32_b64 s24, s[20:21]
	v_cmp_le_u32_e64 s[20:21], s23, v0
	s_bcnt1_i32_b64 s25, s[98:99]
	s_add_i32 s24, s24, s25
	s_bcnt1_i32_b64 s25, s[100:101]
	s_add_i32 s24, s24, s25
	s_bcnt1_i32_b64 s25, s[20:21]
	s_add_i32 s24, s24, s25
	s_cmp_gt_u32 s24, 12
	s_cselect_b32 s96, s23, s96
	s_or_b32 s23, s96, 0x2000000
	v_cmp_le_u32_e64 s[20:21], s23, v2
	v_cmp_le_u32_e64 s[98:99], s23, v5
	v_cmp_le_u32_e64 s[100:101], s23, v4
	s_bcnt1_i32_b64 s24, s[20:21]
	v_cmp_le_u32_e64 s[20:21], s23, v0
	s_bcnt1_i32_b64 s25, s[98:99]
	s_add_i32 s24, s24, s25
	s_bcnt1_i32_b64 s25, s[100:101]
	s_add_i32 s24, s24, s25
	s_bcnt1_i32_b64 s25, s[20:21]
	s_add_i32 s24, s24, s25
	s_cmp_gt_u32 s24, 12
	s_cselect_b32 s96, s23, s96
	s_or_b32 s23, s96, 0x1000000
	v_cmp_le_u32_e64 s[20:21], s23, v2
	v_cmp_le_u32_e64 s[98:99], s23, v5
	v_cmp_le_u32_e64 s[100:101], s23, v4
	s_bcnt1_i32_b64 s24, s[20:21]
	v_cmp_le_u32_e64 s[20:21], s23, v0
	s_bcnt1_i32_b64 s25, s[98:99]
	s_add_i32 s24, s24, s25
	s_bcnt1_i32_b64 s25, s[100:101]
	s_add_i32 s24, s24, s25
	s_bcnt1_i32_b64 s25, s[20:21]
	s_add_i32 s24, s24, s25
	s_cmp_gt_u32 s24, 12
	s_cselect_b32 s96, s23, s96
	s_or_b32 s23, s96, 0x800000
	v_cmp_le_u32_e64 s[20:21], s23, v2
	v_cmp_le_u32_e64 s[98:99], s23, v5
	v_cmp_le_u32_e64 s[100:101], s23, v4
	s_bcnt1_i32_b64 s24, s[20:21]
	v_cmp_le_u32_e64 s[20:21], s23, v0
	s_bcnt1_i32_b64 s25, s[98:99]
	s_add_i32 s24, s24, s25
	s_bcnt1_i32_b64 s25, s[100:101]
	s_add_i32 s24, s24, s25
	s_bcnt1_i32_b64 s25, s[20:21]
	s_add_i32 s24, s24, s25
	s_cmp_gt_u32 s24, 12
	s_cselect_b32 s96, s23, s96
	s_or_b32 s23, s96, 0x400000
	v_cmp_le_u32_e64 s[20:21], s23, v2
	v_cmp_le_u32_e64 s[98:99], s23, v5
	v_cmp_le_u32_e64 s[100:101], s23, v4
	s_bcnt1_i32_b64 s24, s[20:21]
	v_cmp_le_u32_e64 s[20:21], s23, v0
	s_bcnt1_i32_b64 s25, s[98:99]
	s_add_i32 s24, s24, s25
	s_bcnt1_i32_b64 s25, s[100:101]
	s_add_i32 s24, s24, s25
	s_bcnt1_i32_b64 s25, s[20:21]
	s_add_i32 s24, s24, s25
	s_cmp_gt_u32 s24, 12
	s_cselect_b32 s96, s23, s96
	s_or_b32 s23, s96, 0x200000
	v_cmp_le_u32_e64 s[20:21], s23, v2
	v_cmp_le_u32_e64 s[98:99], s23, v5
	v_cmp_le_u32_e64 s[100:101], s23, v4
	s_bcnt1_i32_b64 s24, s[20:21]
	v_cmp_le_u32_e64 s[20:21], s23, v0
	s_bcnt1_i32_b64 s25, s[98:99]
	s_add_i32 s24, s24, s25
	s_bcnt1_i32_b64 s25, s[100:101]
	s_add_i32 s24, s24, s25
	s_bcnt1_i32_b64 s25, s[20:21]
	s_add_i32 s24, s24, s25
	s_cmp_gt_u32 s24, 12
	s_cselect_b32 s96, s23, s96
	s_or_b32 s23, s96, 0x100000
	v_cmp_le_u32_e64 s[20:21], s23, v2
	v_cmp_le_u32_e64 s[98:99], s23, v5
	v_cmp_le_u32_e64 s[100:101], s23, v4
	s_bcnt1_i32_b64 s24, s[20:21]
	v_cmp_le_u32_e64 s[20:21], s23, v0
	s_bcnt1_i32_b64 s25, s[98:99]
	s_add_i32 s24, s24, s25
	s_bcnt1_i32_b64 s25, s[100:101]
	s_add_i32 s24, s24, s25
	s_bcnt1_i32_b64 s25, s[20:21]
	s_add_i32 s24, s24, s25
	s_cmp_gt_u32 s24, 12
	s_cselect_b32 s96, s23, s96
	s_or_b32 s23, s96, 0x80000
	v_cmp_le_u32_e64 s[20:21], s23, v2
	v_cmp_le_u32_e64 s[98:99], s23, v5
	v_cmp_le_u32_e64 s[100:101], s23, v4
	s_bcnt1_i32_b64 s24, s[20:21]
	v_cmp_le_u32_e64 s[20:21], s23, v0
	s_bcnt1_i32_b64 s25, s[98:99]
	s_add_i32 s24, s24, s25
	s_bcnt1_i32_b64 s25, s[100:101]
	s_add_i32 s24, s24, s25
	s_bcnt1_i32_b64 s25, s[20:21]
	s_add_i32 s24, s24, s25
	s_cmp_gt_u32 s24, 12
	s_cselect_b32 s96, s23, s96
	s_or_b32 s23, s96, 0x40000
	v_cmp_le_u32_e64 s[20:21], s23, v2
	v_cmp_le_u32_e64 s[98:99], s23, v5
	v_cmp_le_u32_e64 s[100:101], s23, v4
	s_bcnt1_i32_b64 s24, s[20:21]
	v_cmp_le_u32_e64 s[20:21], s23, v0
	s_bcnt1_i32_b64 s25, s[98:99]
	s_add_i32 s24, s24, s25
	s_bcnt1_i32_b64 s25, s[100:101]
	s_add_i32 s24, s24, s25
	s_bcnt1_i32_b64 s25, s[20:21]
	s_add_i32 s24, s24, s25
	s_cmp_gt_u32 s24, 12
	s_cselect_b32 s96, s23, s96
	s_or_b32 s23, s96, 0x20000
	v_cmp_le_u32_e64 s[20:21], s23, v2
; __device__ __forceinline__ void phase_cmp(const Params& p, LAS unsigned char* lds, const bf16_t* Z, const float* G, const bf16_t* KC, const bf16_t* ACCW, float* ACC, int* IDX, ...
;     ...
; #pragma unroll
;                     for (int i = 0; i < 4; ++i) cnt += __builtin_popcountll(__ballot(ok[i] && v[i] >= trial));
;                     if (cnt >= 13) T = trial; }
	v_cmp_le_u32_e64 s[98:99], s23, v5
	v_cmp_le_u32_e64 s[100:101], s23, v4
	s_bcnt1_i32_b64 s24, s[20:21]
	v_cmp_le_u32_e64 s[20:21], s23, v0
	s_bcnt1_i32_b64 s25, s[98:99]
	s_add_i32 s24, s24, s25
	s_bcnt1_i32_b64 s25, s[100:101]
	s_add_i32 s24, s24, s25
	s_bcnt1_i32_b64 s25, s[20:21]
	s_add_i32 s24, s24, s25
	s_cmp_gt_u32 s24, 12
	s_cselect_b32 s96, s23, s96
	s_or_b32 s23, s96, 0x10000
	v_cmp_le_u32_e64 s[20:21], s23, v2
	v_cmp_le_u32_e64 s[98:99], s23, v5
	v_cmp_le_u32_e64 s[100:101], s23, v4
	s_bcnt1_i32_b64 s24, s[20:21]
	v_cmp_le_u32_e64 s[20:21], s23, v0
	s_bcnt1_i32_b64 s25, s[98:99]
	s_add_i32 s24, s24, s25
	s_bcnt1_i32_b64 s25, s[100:101]
	s_add_i32 s24, s24, s25
	s_bcnt1_i32_b64 s25, s[20:21]
	s_add_i32 s24, s24, s25
	s_cmp_gt_u32 s24, 12
	s_cselect_b32 s96, s23, s96
	s_or_b32 s23, s96, 0x8000
	v_cmp_le_u32_e64 s[20:21], s23, v2
	v_cmp_le_u32_e64 s[98:99], s23, v5
	v_cmp_le_u32_e64 s[100:101], s23, v4
	s_bcnt1_i32_b64 s24, s[20:21]
	v_cmp_le_u32_e64 s[20:21], s23, v0
	s_bcnt1_i32_b64 s25, s[98:99]
	s_add_i32 s24, s24, s25
	s_bcnt1_i32_b64 s25, s[100:101]
	s_add_i32 s24, s24, s25
	s_bcnt1_i32_b64 s25, s[20:21]
	s_add_i32 s24, s24, s25
	s_cmp_gt_u32 s24, 12
	s_cselect_b32 s96, s23, s96
	s_or_b32 s23, s96, 0x4000
	v_cmp_le_u32_e64 s[20:21], s23, v2
	v_cmp_le_u32_e64 s[98:99], s23, v5
	v_cmp_le_u32_e64 s[100:101], s23, v4
	s_bcnt1_i32_b64 s24, s[20:21]
	v_cmp_le_u32_e64 s[20:21], s23, v0
	s_bcnt1_i32_b64 s25, s[98:99]
	s_add_i32 s24, s24, s25
	s_bcnt1_i32_b64 s25, s[100:101]
	s_add_i32 s24, s24, s25
	s_bcnt1_i32_b64 s25, s[20:21]
	s_add_i32 s24, s24, s25
	s_cmp_gt_u32 s24, 12
	s_cselect_b32 s96, s23, s96
	s_or_b32 s23, s96, 0x2000
	v_cmp_le_u32_e64 s[20:21], s23, v2
	v_cmp_le_u32_e64 s[98:99], s23, v5
	v_cmp_le_u32_e64 s[100:101], s23, v4
	s_bcnt1_i32_b64 s24, s[20:21]
	v_cmp_le_u32_e64 s[20:21], s23, v0
	s_bcnt1_i32_b64 s25, s[98:99]
	s_add_i32 s24, s24, s25
	s_bcnt1_i32_b64 s25, s[100:101]
	s_add_i32 s24, s24, s25
	s_bcnt1_i32_b64 s25, s[20:21]
	s_add_i32 s24, s24, s25
	s_cmp_gt_u32 s24, 12
	s_cselect_b32 s96, s23, s96
	s_or_b32 s23, s96, 0x1000
	v_cmp_le_u32_e64 s[20:21], s23, v2
	v_cmp_le_u32_e64 s[98:99], s23, v5
	v_cmp_le_u32_e64 s[100:101], s23, v4
	s_bcnt1_i32_b64 s24, s[20:21]
	v_cmp_le_u32_e64 s[20:21], s23, v0
	s_bcnt1_i32_b64 s25, s[98:99]
	s_add_i32 s24, s24, s25
	s_bcnt1_i32_b64 s25, s[100:101]
	s_add_i32 s24, s24, s25
	s_bcnt1_i32_b64 s25, s[20:21]
	s_add_i32 s24, s24, s25
	s_cmp_gt_u32 s24, 12
	s_cselect_b32 s96, s23, s96
	s_or_b32 s23, s96, 0x800
	v_cmp_le_u32_e64 s[20:21], s23, v2
	v_cmp_le_u32_e64 s[98:99], s23, v5
	v_cmp_le_u32_e64 s[100:101], s23, v4
	s_bcnt1_i32_b64 s24, s[20:21]
	v_cmp_le_u32_e64 s[20:21], s23, v0
	s_bcnt1_i32_b64 s25, s[98:99]
	s_add_i32 s24, s24, s25
	s_bcnt1_i32_b64 s25, s[100:101]
	s_add_i32 s24, s24, s25
	s_bcnt1_i32_b64 s25, s[20:21]
	s_add_i32 s24, s24, s25
	s_cmp_gt_u32 s24, 12
	s_cselect_b32 s96, s23, s96
	s_or_b32 s23, s96, 0x400
	v_cmp_le_u32_e64 s[20:21], s23, v2
	v_cmp_le_u32_e64 s[98:99], s23, v5
	v_cmp_le_u32_e64 s[100:101], s23, v4
	s_bcnt1_i32_b64 s24, s[20:21]
	v_cmp_le_u32_e64 s[20:21], s23, v0
	s_bcnt1_i32_b64 s25, s[98:99]
	s_add_i32 s24, s24, s25
	s_bcnt1_i32_b64 s25, s[100:101]
	s_add_i32 s24, s24, s25
	s_bcnt1_i32_b64 s25, s[20:21]
	s_add_i32 s24, s24, s25
	s_cmp_gt_u32 s24, 12
	s_cselect_b32 s96, s23, s96
	s_or_b32 s23, s96, 0x200
	v_cmp_le_u32_e64 s[20:21], s23, v2
	v_cmp_le_u32_e64 s[98:99], s23, v5
	v_cmp_le_u32_e64 s[100:101], s23, v4
	s_bcnt1_i32_b64 s24, s[20:21]
	v_cmp_le_u32_e64 s[20:21], s23, v0
	s_bcnt1_i32_b64 s25, s[98:99]
	s_add_i32 s24, s24, s25
	s_bcnt1_i32_b64 s25, s[100:101]
	s_add_i32 s24, s24, s25
	s_bcnt1_i32_b64 s25, s[20:21]
	s_add_i32 s24, s24, s25
	s_cmp_gt_u32 s24, 12
	s_cselect_b32 s96, s23, s96
	s_or_b32 s23, s96, 0x100
	v_cmp_le_u32_e64 s[20:21], s23, v2
	v_cmp_le_u32_e64 s[98:99], s23, v5
	v_cmp_le_u32_e64 s[100:101], s23, v4
	s_bcnt1_i32_b64 s24, s[20:21]
	v_cmp_le_u32_e64 s[20:21], s23, v0
	s_bcnt1_i32_b64 s25, s[98:99]
	s_add_i32 s24, s24, s25
	s_bcnt1_i32_b64 s25, s[100:101]
	s_add_i32 s24, s24, s25
	s_bcnt1_i32_b64 s25, s[20:21]
	s_add_i32 s24, s24, s25
	s_cmp_gt_u32 s24, 12
	s_cselect_b32 s96, s23, s96
	s_or_b32 s23, s96, 0x80
	v_cmp_le_u32_e64 s[20:21], s23, v2
; __device__ __forceinline__ void phase_cmp(const Params& p, LAS unsigned char* lds, const bf16_t* Z, const float* G, const bf16_t* KC, const bf16_t* ACCW, float* ACC, int* IDX, ...
;     ...
; #pragma unroll
;                     for (int i = 0; i < 4; ++i) cnt += __builtin_popcountll(__ballot(ok[i] && v[i] >= trial));
;                     if (cnt >= 13) T = trial; }
;                 int n_gt = 0;
; #pragma unroll
;                 for (int i = 0; i < 4; ++i) n_gt += __builtin_popcountll(__ballot(ok[i] && v[i] > T));
;                 int* dst = IDX + (((size_t)b * SEQ + qb * 64 + qi) * 2 + g) * 16;
;                 if (lane == 0) { dst[0] = 0; dst[1] = cur - 1; dst[2] = cur; }
	v_cmp_le_u32_e64 s[98:99], s23, v5
	v_cmp_le_u32_e64 s[100:101], s23, v4
	s_bcnt1_i32_b64 s24, s[20:21]
	v_cmp_le_u32_e64 s[20:21], s23, v0
	s_bcnt1_i32_b64 s25, s[98:99]
	s_add_i32 s24, s24, s25
	s_bcnt1_i32_b64 s25, s[100:101]
	s_add_i32 s24, s24, s25
	s_bcnt1_i32_b64 s25, s[20:21]
	s_add_i32 s24, s24, s25
	s_cmp_gt_u32 s24, 12
	s_cselect_b32 s96, s23, s96
	s_or_b32 s23, s96, 64
	v_cmp_le_u32_e64 s[20:21], s23, v2
	v_cmp_le_u32_e64 s[98:99], s23, v5
	v_cmp_le_u32_e64 s[100:101], s23, v4
	s_bcnt1_i32_b64 s24, s[20:21]
	v_cmp_le_u32_e64 s[20:21], s23, v0
	s_bcnt1_i32_b64 s25, s[98:99]
	s_add_i32 s24, s24, s25
	s_bcnt1_i32_b64 s25, s[100:101]
	s_add_i32 s24, s24, s25
	s_bcnt1_i32_b64 s25, s[20:21]
	s_add_i32 s24, s24, s25
	s_cmp_gt_u32 s24, 12
	s_cselect_b32 s96, s23, s96
	s_or_b32 s23, s96, 32
	v_cmp_le_u32_e64 s[20:21], s23, v2
	v_cmp_le_u32_e64 s[98:99], s23, v5
	v_cmp_le_u32_e64 s[100:101], s23, v4
	s_bcnt1_i32_b64 s24, s[20:21]
	v_cmp_le_u32_e64 s[20:21], s23, v0
	s_bcnt1_i32_b64 s25, s[98:99]
	s_add_i32 s24, s24, s25
	s_bcnt1_i32_b64 s25, s[100:101]
	s_add_i32 s24, s24, s25
	s_bcnt1_i32_b64 s25, s[20:21]
	s_add_i32 s24, s24, s25
	s_cmp_gt_u32 s24, 12
	s_cselect_b32 s96, s23, s96
	s_or_b32 s23, s96, 16
	v_cmp_le_u32_e64 s[20:21], s23, v2
	v_cmp_le_u32_e64 s[98:99], s23, v5
	v_cmp_le_u32_e64 s[100:101], s23, v4
	s_bcnt1_i32_b64 s24, s[20:21]
	v_cmp_le_u32_e64 s[20:21], s23, v0
	s_bcnt1_i32_b64 s25, s[98:99]
	s_add_i32 s24, s24, s25
	s_bcnt1_i32_b64 s25, s[100:101]
	s_add_i32 s24, s24, s25
	s_bcnt1_i32_b64 s25, s[20:21]
	s_add_i32 s24, s24, s25
	s_cmp_gt_u32 s24, 12
	s_cselect_b32 s96, s23, s96
	s_or_b32 s23, s96, 8
	v_cmp_le_u32_e64 s[20:21], s23, v2
	v_cmp_le_u32_e64 s[98:99], s23, v5
	v_cmp_le_u32_e64 s[100:101], s23, v4
	s_bcnt1_i32_b64 s24, s[20:21]
	v_cmp_le_u32_e64 s[20:21], s23, v0
	s_bcnt1_i32_b64 s25, s[98:99]
	s_add_i32 s24, s24, s25
	s_bcnt1_i32_b64 s25, s[100:101]
	s_add_i32 s24, s24, s25
	s_bcnt1_i32_b64 s25, s[20:21]
	s_add_i32 s24, s24, s25
	s_cmp_gt_u32 s24, 12
	s_cselect_b32 s96, s23, s96
	s_or_b32 s23, s96, 4
	v_cmp_le_u32_e64 s[20:21], s23, v2
	v_cmp_le_u32_e64 s[98:99], s23, v5
	v_cmp_le_u32_e64 s[100:101], s23, v4
	s_bcnt1_i32_b64 s24, s[20:21]
	v_cmp_le_u32_e64 s[20:21], s23, v0
	s_bcnt1_i32_b64 s25, s[98:99]
	s_add_i32 s24, s24, s25
	s_bcnt1_i32_b64 s25, s[100:101]
	s_add_i32 s24, s24, s25
	s_bcnt1_i32_b64 s25, s[20:21]
	s_add_i32 s24, s24, s25
	s_cmp_gt_u32 s24, 12
	s_cselect_b32 s96, s23, s96
	s_or_b32 s23, s96, 2
	v_cmp_le_u32_e64 s[20:21], s23, v2
	v_cmp_le_u32_e64 s[98:99], s23, v5
	v_cmp_le_u32_e64 s[100:101], s23, v4
	s_bcnt1_i32_b64 s24, s[20:21]
	v_cmp_le_u32_e64 s[20:21], s23, v0
	s_bcnt1_i32_b64 s25, s[98:99]
	s_add_i32 s24, s24, s25
	s_bcnt1_i32_b64 s25, s[100:101]
	s_add_i32 s24, s24, s25
	s_bcnt1_i32_b64 s25, s[20:21]
	s_add_i32 s24, s24, s25
	s_cmp_gt_u32 s24, 12
	s_cselect_b32 s96, s23, s96
	s_or_b32 s23, s96, 1
	v_cmp_le_u32_e64 s[20:21], s23, v2
	v_cmp_le_u32_e64 s[98:99], s23, v5
	v_cmp_le_u32_e64 s[100:101], s23, v4
	s_bcnt1_i32_b64 s24, s[20:21]
	v_cmp_le_u32_e64 s[20:21], s23, v0
	s_bcnt1_i32_b64 s25, s[98:99]
	s_add_i32 s24, s24, s25
	s_bcnt1_i32_b64 s25, s[100:101]
	s_add_i32 s24, s24, s25
	s_bcnt1_i32_b64 s25, s[20:21]
	s_add_i32 s24, s24, s25
	s_cmp_gt_u32 s24, 12
	s_cselect_b32 s96, s23, s96
	s_mov_b32 s22, -1
	v_cmp_lt_u32_e64 s[20:21], s96, v2
	s_and_b64 s[80:81], s[70:71], s[20:21]
	v_cmp_lt_u32_e64 s[20:21], s96, v5
	s_and_b64 s[78:79], vcc, s[20:21]
	v_cmp_lt_u32_e64 s[20:21], s96, v4
	s_and_b64 s[76:77], s[16:17], s[20:21]
	v_cmp_lt_u32_e64 s[20:21], s96, v0
	s_and_b64 s[74:75], s[18:19], s[20:21]
	s_ashr_i32 s21, s95, 31
	s_add_u32 s20, s95, s26
	s_addc_u32 s21, s21, 0
	s_lshl_b64 s[20:21], s[20:21], 7
	v_cndmask_b32_e64 v3, 0, 1, s[80:81]
	v_cndmask_b32_e64 v8, 0, 1, s[78:79]
	v_cndmask_b32_e64 v7, 0, 1, s[76:77]
	v_cndmask_b32_e64 v6, 0, 1, s[74:75]
	s_add_u32 s72, s92, s20
	v_cmp_ne_u32_e64 s[22:23], 0, v3
	v_cmp_ne_u32_e64 s[24:25], 0, v8
	v_cmp_ne_u32_e64 s[38:39], 0, v7
	v_cmp_ne_u32_e64 s[40:41], 0, v6
	s_addc_u32 s73, s93, s21
	s_and_saveexec_b64 s[20:21], s[8:9]
	s_cbranch_execz .LBB0_436
	v_mov_b32_e32 v11, s94
	v_mov_b32_e32 v12, s91
	v_mov_b32_e32 v10, v1
	global_store_dwordx3 v1, v[10:12], s[72:73]

; __device__ __forceinline__ void rms_row_f32(float* xrow, const float* g, int lane) {
;     f32x4 v[4]; float s = 0.f;
; #pragma unroll
;     for (int j = 0; j < 4; ++j) { v[j] = ((const f32x4*)xrow)[lane + 64 * j]; s += (v[j].x * v[j].x + v[j].y * v[j].y) + (v[j].z * v[j].z + v[j].w * v[j].w); }
;     const float r = rsqrtf(wave_sum(s) * (1.f / DM) + EPSN);
; #pragma unroll
;     for (int j = 0; j < 4; ++j) { const f32x4 gv = ((const f32x4*)g)[lane + 64 * j]; ((f32x4*)xrow)[lane + 64 * j] = v[j] * r * gv; }
; }
; __global__ void __launch_bounds__(512, 2) hybrid_fwd(Params p_unused) {
;     ...
;         if (RUN(pb + 8) && layer == 1) {
;             { PHASE_ARGS
;             for (int m = P.bid * 8 + wid; m < NT; m += P.gdim * 8) rms_row_f32(P.out + (size_t)m * DM, P.final_norm, lane); }
.LBB0_1127:
	s_cmp_le_i32 s88, s18
	s_cselect_b64 s[2:3], -1, 0
	s_cmp_lt_i32 s18, s89
	v_readlane_b32 s6, v255, 4
	s_cselect_b64 s[4:5], -1, 0
	v_readlane_b32 s7, v255, 5
	s_and_b64 s[4:5], s[6:7], s[4:5]
	s_and_b64 s[2:3], s[2:3], s[4:5]
	s_andn2_b64 vcc, exec, s[2:3]
	s_cbranch_vccnz .LBB0_81
	s_mov_b64 s[2:3], s[0:1]
	v_readlane_b32 s6, v254, 0
	s_mov_b32 s4, s86
	v_mov_b32_e32 v0, v187
	s_lshl_b32 s7, s6, 3
	v_readfirstlane_b32 s5, v0
	s_ashr_i32 s5, s5, 6
	s_add_i32 s6, s5, s7
	s_cmpk_gt_i32 s6, 0x7fff
	s_cbranch_scc1 .LBB0_81
	v_and_b32_e32 v2, 64, v244
	v_add_u32_e32 v2, 64, v2
	s_waitcnt lgkmcnt(0)
	v_xor_b32_e32 v3, 1, v244
	v_cmp_lt_i32_e32 vcc, v3, v2
	s_load_dwordx4 s[8:11], s[2:3], 0x78
	v_and_b32_e32 v0, 63, v0
	v_cndmask_b32_e32 v3, v244, v3, vcc
	s_waitcnt vmcnt(0)
	v_lshlrev_b32_e32 v22, 2, v3
	v_xor_b32_e32 v3, 2, v244
	v_cmp_lt_i32_e32 vcc, v3, v2
	v_lshlrev_b32_e32 v0, 4, v0
	s_waitcnt lgkmcnt(0)
	v_lshl_add_u64 v[18:19], s[8:9], 0, v[0:1]
	v_cndmask_b32_e32 v3, v244, v3, vcc
	v_lshlrev_b32_e32 v23, 2, v3
	v_xor_b32_e32 v3, 4, v244
	v_cmp_lt_i32_e32 vcc, v3, v2
	s_lshl_b32 s2, s4, 3
	s_ashr_i32 s3, s5, 31
	v_cndmask_b32_e32 v3, v244, v3, vcc
	v_lshlrev_b32_e32 v24, 2, v3
	v_xor_b32_e32 v3, 8, v244
	v_cmp_lt_i32_e32 vcc, v3, v2
	s_ashr_i32 s8, s7, 31
	s_add_u32 s4, s5, s7
	v_cndmask_b32_e32 v3, v244, v3, vcc
	v_lshlrev_b32_e32 v25, 2, v3
	v_xor_b32_e32 v3, 16, v244
	v_cmp_lt_i32_e32 vcc, v3, v2
	s_addc_u32 s5, s3, s8
	s_lshl_b64 s[4:5], s[4:5], 12
	v_cndmask_b32_e32 v3, v244, v3, vcc
	v_lshlrev_b32_e32 v26, 2, v3
	v_xor_b32_e32 v3, 32, v244
	v_cmp_lt_i32_e32 vcc, v3, v2
	s_add_u32 s4, s10, s4
	s_addc_u32 s5, s11, s5
	v_cndmask_b32_e32 v2, v244, v3, vcc
	v_lshlrev_b32_e32 v27, 2, v2
	v_lshl_add_u64 v[2:3], s[4:5], 0, v[0:1]
	s_mov_b64 s[4:5], 0xc00
	s_ashr_i32 s3, s2, 31
	v_lshl_add_u64 v[20:21], v[2:3], 0, s[4:5]
	s_lshl_b64 s[4:5], s[2:3], 12
	global_load_dwordx4 v[76:79], v[18:19], off
	global_load_dwordx4 v[80:83], v[18:19], off offset:1024
	global_load_dwordx4 v[84:87], v[18:19], off offset:2048
	global_load_dwordx4 v[88:91], v[18:19], off offset:3072
	s_waitcnt vmcnt(0)
.LBB0_1130:
	global_load_dwordx4 v[60:63], v[20:21], off offset:-3072
	global_load_dwordx4 v[64:67], v[20:21], off offset:-2048
	global_load_dwordx4 v[68:71], v[20:21], off offset:-1024
	global_load_dwordx4 v[72:75], v[20:21], off
	s_add_i32 s6, s6, s2
	s_cmp_lt_i32 s6, 0x8000
	s_waitcnt vmcnt(3)
	v_mov_b32_e32 v2, v60
	v_mov_b32_e32 v3, v61
	v_mov_b32_e32 v4, v62
	v_mov_b32_e32 v5, v63
	v_pk_mul_f32 v[6:7], v[4:5], v[4:5]
	v_pk_mul_f32 v[8:9], v[2:3], v[2:3]
	s_nop 0
	v_pk_mov_b32 v[10:11], v[8:9], v[6:7] op_sel:[1,0]
	v_mov_b32_e32 v9, v7
	v_pk_add_f32 v[28:29], v[10:11], v[8:9]
	s_waitcnt vmcnt(2)
	v_mov_b32_e32 v10, v64
	v_mov_b32_e32 v11, v65
	v_mov_b32_e32 v12, v66
	v_mov_b32_e32 v13, v67
	v_pk_add_f32 v[28:29], v[28:29], v[28:29] op_sel:[0,1] op_sel_hi:[1,0]
	v_pk_mul_f32 v[6:7], v[12:13], v[12:13]
	v_pk_mul_f32 v[8:9], v[10:11], v[10:11]
	s_nop 0
	v_pk_mov_b32 v[14:15], v[8:9], v[6:7] op_sel:[1,0]
	v_mov_b32_e32 v9, v7
	v_pk_add_f32 v[30:31], v[14:15], v[8:9]
	s_waitcnt vmcnt(0)
	v_mov_b32_e32 v6, v68
	v_mov_b32_e32 v7, v69
	v_mov_b32_e32 v8, v70
	v_mov_b32_e32 v9, v71
	v_mov_b32_e32 v14, v72
	v_mov_b32_e32 v15, v73
	v_mov_b32_e32 v16, v74
	v_mov_b32_e32 v17, v75
	v_pk_add_f32 v[30:31], v[30:31], v[30:31] op_sel:[0,1] op_sel_hi:[1,0]
	v_mul_f32_e32 v0, v14, v14
	v_mul_f32_e32 v32, v15, v15
	v_mov_b32_e32 v29, v0
	v_mov_b32_e32 v31, v32
	v_mul_f32_e32 v0, v7, v7
	v_mul_f32_e32 v33, v16, v16
	v_pk_add_f32 v[28:29], v[28:29], v[30:31]
	v_pk_fma_f32 v[30:31], v[6:7], v[6:7], v[0:1] op_sel_hi:[1,1,0]
	v_mul_f32_e32 v0, v9, v9
	v_mul_f32_e32 v34, v17, v17
	v_mov_b32_e32 v31, v33
	v_pk_fma_f32 v[32:33], v[8:9], v[8:9], v[0:1] op_sel_hi:[1,1,0]
	s_nop 0
	v_mov_b32_e32 v33, v34
	v_pk_add_f32 v[30:31], v[30:31], v[32:33]
	s_nop 0
	v_pk_add_f32 v[28:29], v[28:29], v[30:31]
	s_nop 0
	v_add_f32_e32 v0, v28, v29
	ds_bpermute_b32 v28, v22, v0
	s_waitcnt lgkmcnt(0)
	v_add_f32_e32 v0, v0, v28
	ds_bpermute_b32 v28, v23, v0
	s_waitcnt lgkmcnt(0)
	v_add_f32_e32 v0, v0, v28
	ds_bpermute_b32 v28, v24, v0
	s_waitcnt lgkmcnt(0)
	v_add_f32_e32 v0, v0, v28
	ds_bpermute_b32 v28, v25, v0
	s_waitcnt lgkmcnt(0)
	v_add_f32_e32 v0, v0, v28
	ds_bpermute_b32 v28, v26, v0
	s_waitcnt lgkmcnt(0)
	v_add_f32_e32 v0, v0, v28
	ds_bpermute_b32 v28, v27, v0
	s_waitcnt lgkmcnt(0)
	v_add_f32_e32 v0, v0, v28
	v_fmamk_f32 v0, v0, 0x3a800000, v238
	v_cmp_gt_f32_e32 vcc, s63, v0
	v_mul_f32_e32 v28, 0x4b800000, v0
	s_nop 0
	v_cndmask_b32_e32 v0, v0, v28, vcc
	v_rsq_f32_e32 v0, v0
	s_nop 0
	v_mul_f32_e32 v28, 0x45800000, v0
	v_cndmask_b32_e32 v0, v0, v28, vcc
	v_pk_mul_f32 v[2:3], v[2:3], v[0:1] op_sel_hi:[1,0]
	v_pk_mul_f32 v[4:5], v[4:5], v[0:1] op_sel_hi:[1,0]
	v_pk_mul_f32 v[12:13], v[12:13], v[0:1] op_sel_hi:[1,0]
	v_pk_mul_f32 v[10:11], v[10:11], v[0:1] op_sel_hi:[1,0]
	v_pk_mul_f32 v[8:9], v[8:9], v[0:1] op_sel_hi:[1,0]
	v_pk_mul_f32 v[6:7], v[6:7], v[0:1] op_sel_hi:[1,0]
	v_pk_mul_f32 v[4:5], v[78:79], v[4:5]
	v_pk_mul_f32 v[2:3], v[76:77], v[2:3]
	global_store_dwordx4 v[20:21], v[2:5], off offset:-3072
	v_pk_mul_f32 v[10:11], v[80:81], v[10:11]
	v_pk_mul_f32 v[12:13], v[82:83], v[12:13]
	global_store_dwordx4 v[20:21], v[10:13], off offset:-2048
	v_pk_mul_f32 v[6:7], v[84:85], v[6:7]
	v_pk_mul_f32 v[8:9], v[86:87], v[8:9]
	global_store_dwordx4 v[20:21], v[6:9], off offset:-1024
	v_pk_mul_f32 v[16:17], v[16:17], v[0:1] op_sel_hi:[1,0]
	v_pk_mul_f32 v[14:15], v[14:15], v[0:1] op_sel_hi:[1,0]
	v_pk_mul_f32 v[16:17], v[90:91], v[16:17]
	v_pk_mul_f32 v[14:15], v[88:89], v[14:15]
	global_store_dwordx4 v[20:21], v[14:17], off
	v_lshl_add_u64 v[20:21], v[20:21], 0, s[4:5]
	s_cbranch_scc1 .LBB0_1130
	s_branch .LBB0_81
